# in-projection GEMM K-loop duplicated per wave half: waves 4-7 run the same phase flips one priority level higher (2/1 instead of 1/0)
# baseline (speedup 1.0000x reference)
; #define PG8_STAGE(bufoff, gbase, voff) do { _Pragma("unroll") for (int _i = 0; _i < 2; ++_i) \
;         __builtin_amdgcn_global_load_lds((const unsigned*)((const char*)(gbase) + (voff)[_i]), (LAS unsigned*)(lds + (bufoff) + ldsw + _i * 8192), 16, 0, 0); } while (0)
; #define PG8_LDA(dst, b, h) do { _Pragma("unroll") for (int m = 0; m < 4; ++m) _Pragma("unroll") for (int k = 0; k < 2; ++k) dst[m][k] = *(const LAS bf16x8*)(lds + PG8_SA(b, h) + aoff + m * 2048 + k * 1024); } while (0)
; #define PG8_BAR __builtin_amdgcn_s_barrier()
; DI void gemm_phase(LAS unsigned char* lds, const Gemm g, const StaticOrder& S, const EpiBf16& E) {
;     ...
;     Unit cur, nxt; int ui = 0;
;     if (!S.next(0, cur)) return;
;     f32x4 acc[2][2][4][2];
; #pragma unroll
;     for (int a = 0; a < 2; ++a)
; #pragma unroll
;         for (int b = 0; b < 2; ++b)
; #pragma unroll
;             for (int m = 0; m < 4; ++m)
; #pragma unroll
;                 for (int n = 0; n < 2; ++n) acc[a][b][m][n] = (f32x4){0.f, 0.f, 0.f, 0.f};
;     bf16x8 At[4][2], B0[2][2], B1[2][2];
;     const char* cA = (const char*)g.A + (size_t)cur.pm * tstep; const char* cB = (const char*)g.Bt + (size_t)cur.pn * tstep;
;     PG8_STAGE(PG8_SB(0, 0), cB, voffB); PG8_STAGE(PG8_SA(0, 0), cA, voffA); PG8_STAGE(PG8_SB(0, 1), cB + hstep, voffB); PG8_STAGE(PG8_SA(0, 1), cA + hstep, voffA);
;     if (wr == 1) PG8_BAR;
;     PG8_WAIT_V(4); PG8_BAR;
;     PG8_STAGE(PG8_SB(1, 0), cB + kstep, voffB); PG8_STAGE(PG8_SA(1, 0), cA + kstep, voffA); PG8_STAGE(PG8_SB(1, 1), cB + hstep + kstep, voffB);
;     PG8_WAIT_V(6); PG8_BAR;
;     for (;;) {
;         const bool has_next = S.next(ui + 1, nxt);
;         const char* nA = has_next ? (const char*)g.A + (size_t)nxt.pm * tstep : cA; const char* nB = has_next ? (const char*)g.Bt + (size_t)nxt.pn * tstep : cB;
;         for (int t = 0; t < nt; t += 2) {
;             const bool last = (t == nt - 2);
;             const char* a1 = cA + (size_t)(t + 1) * kstep;
;             const char* a2 = last ? nA : cA + (size_t)(t + 2) * kstep; const char* b2 = last ? nB : cB + (size_t)(t + 2) * kstep;
;             const char* a3 = a2 + kstep; const char* b3 = b2 + kstep;
;             PG8_LDB(B0, 0, 0); PG8_SCHED; PG8_LDA(At, 0, 0); PG8_STAGE(PG8_SA(1, 1), a1 + hstep, voffA);
;             PG8_WAIT_L(8); PG8_BAR; PG8_WAIT_L(0); PG8_MMA(0, 0, At, B0); PG8_BAR; PG8_SCHED;
.LBB0_180:
	v_mov_b64_e32 v[0:1], 0x3f0
	s_ashr_i32 s45, s44, 31
	v_cmp_lt_i64_e32 vcc, s[46:47], v[0:1]
	s_lshl_b64 s[46:47], s[44:45], 20
	s_add_u32 s46, s21, s46
	s_addc_u32 s47, s22, s47
	s_and_b64 s[48:49], vcc, exec
	s_cselect_b32 s45, s47, s51
	s_cselect_b32 s69, s46, s50
	s_ashr_i32 s43, s42, 31
	s_lshl_b64 s[48:49], s[42:43], 20
	s_add_u32 s48, s24, s48
	s_addc_u32 s49, s26, s49
	s_and_b64 s[54:55], vcc, exec
	s_cselect_b32 s43, s49, s53
	s_cselect_b32 s70, s48, s52
	s_add_u32 s50, s50, 0x80080
	s_addc_u32 s51, s51, 0
	s_add_u32 s71, s52, 0x100
	v_mov_b32_e32 v0, 0
	s_addc_u32 s72, s53, 0
	s_mov_b32 s73, -2
	v_mov_b32_e32 v1, v0
	v_mov_b32_e32 v2, v0
	v_mov_b32_e32 v3, v0
	v_mov_b32_e32 v4, v0
	v_mov_b32_e32 v5, v0
	v_mov_b32_e32 v6, v0
	v_mov_b32_e32 v7, v0
	v_mov_b32_e32 v8, v0
	v_mov_b32_e32 v9, v0
	v_mov_b32_e32 v10, v0
	v_mov_b32_e32 v11, v0
	v_mov_b32_e32 v12, v0
	v_mov_b32_e32 v13, v0
	v_mov_b32_e32 v14, v0
	v_mov_b32_e32 v15, v0
	v_mov_b32_e32 v24, v0
	v_mov_b32_e32 v25, v0
	v_mov_b32_e32 v26, v0
	v_mov_b32_e32 v27, v0
	v_mov_b32_e32 v28, v0
	v_mov_b32_e32 v29, v0
	v_mov_b32_e32 v30, v0
	v_mov_b32_e32 v31, v0
	v_mov_b32_e32 v40, v0
	v_mov_b32_e32 v41, v0
	v_mov_b32_e32 v42, v0
	v_mov_b32_e32 v43, v0
	v_mov_b32_e32 v44, v0
	v_mov_b32_e32 v45, v0
	v_mov_b32_e32 v46, v0
	v_mov_b32_e32 v47, v0
	v_mov_b32_e32 v16, v0
	v_mov_b32_e32 v17, v0
	v_mov_b32_e32 v18, v0
	v_mov_b32_e32 v19, v0
	v_mov_b32_e32 v20, v0
	v_mov_b32_e32 v21, v0
	v_mov_b32_e32 v22, v0
	v_mov_b32_e32 v23, v0
	v_mov_b32_e32 v32, v0
	v_mov_b32_e32 v33, v0
	v_mov_b32_e32 v34, v0
	v_mov_b32_e32 v35, v0
	v_mov_b32_e32 v36, v0
	v_mov_b32_e32 v37, v0
	v_mov_b32_e32 v38, v0
	v_mov_b32_e32 v39, v0
	v_mov_b32_e32 v48, v0
	v_mov_b32_e32 v49, v0
	v_mov_b32_e32 v50, v0
	v_mov_b32_e32 v51, v0
	v_mov_b32_e32 v52, v0
	v_mov_b32_e32 v53, v0
	v_mov_b32_e32 v54, v0
	v_mov_b32_e32 v55, v0
	v_mov_b32_e32 v56, v0
	v_mov_b32_e32 v57, v0
	v_mov_b32_e32 v58, v0
	v_mov_b32_e32 v59, v0
	v_mov_b32_e32 v60, v0
	v_mov_b32_e32 v61, v0
	v_mov_b32_e32 v62, v0
	v_mov_b32_e32 v63, v0
	v_mov_b32_e32 v64, v0
	v_mov_b32_e32 v65, v0
	v_mov_b32_e32 v66, v0
	v_mov_b32_e32 v67, v0
	v_mov_b32_e32 v68, v0
	v_mov_b32_e32 v69, v0
	v_mov_b32_e32 v70, v0
	v_mov_b32_e32 v71, v0
	v_mov_b32_e32 v72, v0
	v_mov_b32_e32 v73, v0
	v_mov_b32_e32 v74, v0
	v_mov_b32_e32 v75, v0
	v_mov_b32_e32 v76, v0
	v_mov_b32_e32 v77, v0
	v_mov_b32_e32 v78, v0
	v_mov_b32_e32 v79, v0
	v_mov_b32_e32 v88, v0
	v_mov_b32_e32 v89, v0
	v_mov_b32_e32 v90, v0
	v_mov_b32_e32 v91, v0
	v_mov_b32_e32 v92, v0
	v_mov_b32_e32 v93, v0
	v_mov_b32_e32 v94, v0
	v_mov_b32_e32 v95, v0
	v_mov_b32_e32 v104, v0
	v_mov_b32_e32 v105, v0
	v_mov_b32_e32 v106, v0
	v_mov_b32_e32 v107, v0
	v_mov_b32_e32 v108, v0
	v_mov_b32_e32 v109, v0
	v_mov_b32_e32 v110, v0
	v_mov_b32_e32 v111, v0
	v_mov_b32_e32 v80, v0
	v_mov_b32_e32 v81, v0
	v_mov_b32_e32 v82, v0
	v_mov_b32_e32 v83, v0
	v_mov_b32_e32 v84, v0
	v_mov_b32_e32 v85, v0
	v_mov_b32_e32 v86, v0
	v_mov_b32_e32 v87, v0
	v_mov_b32_e32 v96, v0
	v_mov_b32_e32 v97, v0
	v_mov_b32_e32 v98, v0
	v_mov_b32_e32 v99, v0
	v_mov_b32_e32 v100, v0
	v_mov_b32_e32 v101, v0
	v_mov_b32_e32 v102, v0
	v_mov_b32_e32 v103, v0
	v_mov_b32_e32 v112, v0
	v_mov_b32_e32 v113, v0
	v_mov_b32_e32 v114, v0
	v_mov_b32_e32 v115, v0
	v_mov_b32_e32 v116, v0
	v_mov_b32_e32 v117, v0
	v_mov_b32_e32 v118, v0
	v_mov_b32_e32 v119, v0
	v_mov_b32_e32 v120, v0
	v_mov_b32_e32 v121, v0
	v_mov_b32_e32 v122, v0
	v_mov_b32_e32 v123, v0
	v_mov_b32_e32 v124, v0
	v_mov_b32_e32 v125, v0
	v_mov_b32_e32 v126, v0
	v_mov_b32_e32 v127, v0
	v_readfirstlane_b32 s98, v166
	s_nop 0
	s_lshr_b32 s98, s98, 6
	s_cmp_ge_u32 s98, 4
	s_cbranch_scc1 .Lg1_young
.LBB0_181:
	ds_read_b128 v[160:163], v155
	ds_read_b128 v[184:187], v155 offset:1024
	ds_read_b128 v[188:191], v155 offset:2048
	ds_read_b128 v[192:195], v155 offset:3072
	s_add_u32 s4, s50, 0xfff80080
	s_addc_u32 s5, s51, -1
	s_cmp_eq_u32 s73, 28
	s_cselect_b32 s55, s45, s5
	s_cselect_b32 s54, s69, s4
	s_cselect_b32 s53, s43, s72
	s_cselect_b32 s52, s70, s71
	v_lshl_add_u64 v[164:165], s[50:51], 0, v[148:149]
	s_add_i32 m0, s31, 0xc000
	ds_read_b128 v[196:199], v156
	ds_read_b128 v[200:203], v156 offset:1024
	ds_read_b128 v[204:207], v156 offset:2048
	ds_read_b128 v[208:211], v156 offset:3072
	ds_read_b128 v[212:215], v156 offset:4096
	ds_read_b128 v[216:219], v156 offset:5120
	ds_read_b128 v[224:227], v156 offset:6144
	ds_read_b128 v[228:231], v156 offset:7168
	global_load_lds_dwordx4 v[164:165], off
	v_lshl_add_u64 v[164:165], s[50:51], 0, v[150:151]
	s_add_i32 m0, s31, 0xe000
	s_nop 0
	global_load_lds_dwordx4 v[164:165], off
	s_waitcnt lgkmcnt(8)
	s_barrier
	s_waitcnt lgkmcnt(0)
	s_setprio 1
	s_waitcnt lgkmcnt(0)
	v_mfma_f32_16x16x32_bf16 v[124:127], v[160:163], v[196:199], v[124:127]
	v_mfma_f32_16x16x32_bf16 v[120:123], v[188:191], v[196:199], v[120:123]
	v_mfma_f32_16x16x32_bf16 v[116:119], v[160:163], v[204:207], v[116:119]
	v_mfma_f32_16x16x32_bf16 v[112:115], v[188:191], v[204:207], v[112:115]
	v_mfma_f32_16x16x32_bf16 v[100:103], v[160:163], v[212:215], v[100:103]
	v_mfma_f32_16x16x32_bf16 v[96:99], v[188:191], v[212:215], v[96:99]
	v_mfma_f32_16x16x32_bf16 v[84:87], v[160:163], v[224:227], v[84:87]
	v_mfma_f32_16x16x32_bf16 v[80:83], v[188:191], v[224:227], v[80:83]
	v_mfma_f32_16x16x32_bf16 v[124:127], v[184:187], v[200:203], v[124:127]
	v_mfma_f32_16x16x32_bf16 v[120:123], v[192:195], v[200:203], v[120:123]
	v_mfma_f32_16x16x32_bf16 v[116:119], v[184:187], v[208:211], v[116:119]
	v_mfma_f32_16x16x32_bf16 v[112:115], v[192:195], v[208:211], v[112:115]
	v_mfma_f32_16x16x32_bf16 v[100:103], v[184:187], v[216:219], v[100:103]
	v_mfma_f32_16x16x32_bf16 v[96:99], v[192:195], v[216:219], v[96:99]
	v_mfma_f32_16x16x32_bf16 v[84:87], v[184:187], v[228:231], v[84:87]
	v_mfma_f32_16x16x32_bf16 v[80:83], v[192:195], v[228:231], v[80:83]
	s_setprio 0
	s_barrier
; #define PG8_STAGE(bufoff, gbase, voff) do { _Pragma("unroll") for (int _i = 0; _i < 2; ++_i) \
;         __builtin_amdgcn_global_load_lds((const unsigned*)((const char*)(gbase) + (voff)[_i]), (LAS unsigned*)(lds + (bufoff) + ldsw + _i * 8192), 16, 0, 0); } while (0)
; #define PG8_LDA(dst, b, h) do { _Pragma("unroll") for (int m = 0; m < 4; ++m) _Pragma("unroll") for (int k = 0; k < 2; ++k) dst[m][k] = *(const LAS bf16x8*)(lds + PG8_SA(b, h) + aoff + m * 2048 + k * 1024); } while (0)
; #define PG8_LDB(dst, b, h) do { _Pragma("unroll") for (int n = 0; n < 2; ++n) _Pragma("unroll") for (int k = 0; k < 2; ++k) dst[n][k] = *(const LAS bf16x8*)(lds + PG8_SB(b, h) + boff + n * 2048 + k * 1024); } while (0)
; #define PG8_MMA(ai, bj, At, Bt) do { __builtin_amdgcn_s_setprio(1); _Pragma("unroll") for (int m = 0; m < 4; ++m) _Pragma("unroll") for (int n = 0; n < 2; ++n) _Pragma("unroll") for (int k = 0; k < 2; ++k) \
;         acc[ai][bj][m][n] = __builtin_amdgcn_mfma_f32_16x16x32_bf16(Bt[n][k], At[m][k], acc[ai][bj][m][n], 0, 0, 0); __builtin_amdgcn_s_setprio(0); } while (0)
; #define PG8_WAIT_V(n) asm volatile("s_waitcnt vmcnt(" #n ")" ::: "memory")
; #define PG8_WAIT_L(n) asm volatile("s_waitcnt lgkmcnt(" #n ")" ::: "memory")
; #define PG8_BAR __builtin_amdgcn_s_barrier()
; #define PG8_SCHED __builtin_amdgcn_sched_barrier(0)
; DI void gemm_phase(LAS unsigned char* lds, const Gemm g, const StaticOrder& S, const EpiBf16& E) {
;     ...
;             PG8_LDB(B1, 0, 1); PG8_STAGE(PG8_SB(0, 0), b2, voffB);
;             PG8_BAR; PG8_WAIT_L(0); PG8_MMA(0, 1, At, B1); PG8_BAR;
;             PG8_LDA(At, 0, 1); PG8_STAGE(PG8_SA(0, 0), a2, voffA);
;             PG8_BAR; PG8_WAIT_L(0); PG8_MMA(1, 0, At, B0); PG8_BAR; PG8_SCHED;
;             PG8_STAGE(PG8_SB(0, 1), b2 + hstep, voffB);
;             PG8_WAIT_V(6); PG8_BAR; PG8_MMA(1, 1, At, B1); PG8_BAR;
;             PG8_LDB(B0, 1, 0); PG8_SCHED; PG8_LDA(At, 1, 0); PG8_STAGE(PG8_SA(0, 1), a2 + hstep, voffA);
;             PG8_WAIT_L(8); PG8_BAR; PG8_WAIT_L(0); PG8_MMA(0, 0, At, B0); PG8_BAR; PG8_SCHED;
	s_mov_b32 m0, s28
	v_lshl_add_u64 v[164:165], s[52:53], 0, v[132:133]
	ds_read_b128 v[232:235], v157
	ds_read_b128 v[236:239], v157 offset:1024
	ds_read_b128 v[240:243], v157 offset:2048
	ds_read_b128 v[244:247], v157 offset:3072
	global_load_lds_dwordx4 v[164:165], off
	v_lshl_add_u64 v[248:249], s[52:53], 0, v[142:143]
	s_mov_b32 m0, s30
	s_nop 0
	global_load_lds_dwordx4 v[248:249], off
	s_barrier
	s_waitcnt lgkmcnt(0)
	s_setprio 1
	s_waitcnt lgkmcnt(0)
	v_mfma_f32_16x16x32_bf16 v[108:111], v[232:235], v[196:199], v[108:111]
	v_mfma_f32_16x16x32_bf16 v[104:107], v[240:243], v[196:199], v[104:107]
	v_mfma_f32_16x16x32_bf16 v[92:95], v[232:235], v[204:207], v[92:95]
	v_mfma_f32_16x16x32_bf16 v[88:91], v[240:243], v[204:207], v[88:91]
	v_mfma_f32_16x16x32_bf16 v[76:79], v[232:235], v[212:215], v[76:79]
	v_mfma_f32_16x16x32_bf16 v[72:75], v[240:243], v[212:215], v[72:75]
	v_mfma_f32_16x16x32_bf16 v[68:71], v[232:235], v[224:227], v[68:71]
	v_mfma_f32_16x16x32_bf16 v[64:67], v[240:243], v[224:227], v[64:67]
	v_mfma_f32_16x16x32_bf16 v[108:111], v[236:239], v[200:203], v[108:111]
	v_mfma_f32_16x16x32_bf16 v[104:107], v[244:247], v[200:203], v[104:107]
	v_mfma_f32_16x16x32_bf16 v[92:95], v[236:239], v[208:211], v[92:95]
	v_mfma_f32_16x16x32_bf16 v[88:91], v[244:247], v[208:211], v[88:91]
	v_mfma_f32_16x16x32_bf16 v[76:79], v[236:239], v[216:219], v[76:79]
	v_mfma_f32_16x16x32_bf16 v[72:75], v[244:247], v[216:219], v[72:75]
	v_mfma_f32_16x16x32_bf16 v[68:71], v[236:239], v[228:231], v[68:71]
	v_mfma_f32_16x16x32_bf16 v[64:67], v[244:247], v[228:231], v[64:67]
	s_setprio 0
	s_mov_b32 m0, s31
	v_lshl_add_u64 v[250:251], s[54:55], 0, v[146:147]
	s_barrier
	ds_read_b128 v[196:199], v156 offset:16384
	ds_read_b128 v[200:203], v156 offset:17408
	ds_read_b128 v[204:207], v156 offset:18432
	ds_read_b128 v[208:211], v156 offset:19456
	ds_read_b128 v[212:215], v156 offset:20480
	ds_read_b128 v[216:219], v156 offset:21504
	ds_read_b128 v[224:227], v156 offset:22528
	ds_read_b128 v[228:231], v156 offset:23552
	global_load_lds_dwordx4 v[250:251], off
	v_lshl_add_u64 v[134:135], s[54:55], 0, v[144:145]
	s_mov_b32 m0, s41
	s_nop 0
	global_load_lds_dwordx4 v[134:135], off
	s_barrier
	s_waitcnt lgkmcnt(0)
	s_setprio 1
	s_waitcnt lgkmcnt(0)
	v_mfma_f32_16x16x32_bf16 v[60:63], v[160:163], v[196:199], v[60:63]
	v_mfma_f32_16x16x32_bf16 v[56:59], v[188:191], v[196:199], v[56:59]
	v_mfma_f32_16x16x32_bf16 v[52:55], v[160:163], v[204:207], v[52:55]
	v_mfma_f32_16x16x32_bf16 v[48:51], v[188:191], v[204:207], v[48:51]
	v_mfma_f32_16x16x32_bf16 v[36:39], v[160:163], v[212:215], v[36:39]
	v_mfma_f32_16x16x32_bf16 v[32:35], v[188:191], v[212:215], v[32:35]
	v_mfma_f32_16x16x32_bf16 v[20:23], v[160:163], v[224:227], v[20:23]
	v_mfma_f32_16x16x32_bf16 v[16:19], v[188:191], v[224:227], v[16:19]
	v_mfma_f32_16x16x32_bf16 v[60:63], v[184:187], v[200:203], v[60:63]
	v_mfma_f32_16x16x32_bf16 v[56:59], v[192:195], v[200:203], v[56:59]
	v_mfma_f32_16x16x32_bf16 v[52:55], v[184:187], v[208:211], v[52:55]
	v_mfma_f32_16x16x32_bf16 v[48:51], v[192:195], v[208:211], v[48:51]
	v_mfma_f32_16x16x32_bf16 v[36:39], v[184:187], v[216:219], v[36:39]
	v_mfma_f32_16x16x32_bf16 v[32:35], v[192:195], v[216:219], v[32:35]
	v_mfma_f32_16x16x32_bf16 v[20:23], v[184:187], v[228:231], v[20:23]
	v_mfma_f32_16x16x32_bf16 v[16:19], v[192:195], v[228:231], v[16:19]
	s_setprio 0
	s_barrier
	s_add_u32 s74, s52, 0x80000
	s_addc_u32 s75, s53, 0
	s_mov_b32 m0, s56
	v_lshl_add_u64 v[160:161], s[74:75], 0, v[132:133]
	global_load_lds_dwordx4 v[160:161], off
	v_lshl_add_u64 v[160:161], s[74:75], 0, v[142:143]
	s_mov_b32 m0, s57
	s_nop 0
	global_load_lds_dwordx4 v[160:161], off
	s_waitcnt vmcnt(6)
	s_barrier
	s_setprio 1
	v_mfma_f32_16x16x32_bf16 v[44:47], v[232:235], v[196:199], v[44:47]
	v_mfma_f32_16x16x32_bf16 v[40:43], v[240:243], v[196:199], v[40:43]
	v_mfma_f32_16x16x32_bf16 v[28:31], v[232:235], v[204:207], v[28:31]
	v_mfma_f32_16x16x32_bf16 v[24:27], v[240:243], v[204:207], v[24:27]
	v_mfma_f32_16x16x32_bf16 v[12:15], v[232:235], v[212:215], v[12:15]
	v_mfma_f32_16x16x32_bf16 v[8:11], v[240:243], v[212:215], v[8:11]
	v_mfma_f32_16x16x32_bf16 v[4:7], v[232:235], v[224:227], v[4:7]
	v_mfma_f32_16x16x32_bf16 v[0:3], v[240:243], v[224:227], v[0:3]
	v_mfma_f32_16x16x32_bf16 v[44:47], v[236:239], v[200:203], v[44:47]
	v_mfma_f32_16x16x32_bf16 v[40:43], v[244:247], v[200:203], v[40:43]
	v_mfma_f32_16x16x32_bf16 v[28:31], v[236:239], v[208:211], v[28:31]
	v_mfma_f32_16x16x32_bf16 v[24:27], v[244:247], v[208:211], v[24:27]
	v_mfma_f32_16x16x32_bf16 v[12:15], v[236:239], v[216:219], v[12:15]
	v_mfma_f32_16x16x32_bf16 v[8:11], v[244:247], v[216:219], v[8:11]
	v_mfma_f32_16x16x32_bf16 v[4:7], v[236:239], v[228:231], v[4:7]
	v_mfma_f32_16x16x32_bf16 v[0:3], v[244:247], v[228:231], v[0:3]
	s_setprio 0
	s_barrier
	ds_read_b128 v[160:163], v158
	ds_read_b128 v[184:187], v158 offset:1024
	ds_read_b128 v[188:191], v158 offset:2048
	ds_read_b128 v[192:195], v158 offset:3072
	s_add_u32 s54, s54, 0x80000
	s_addc_u32 s55, s55, 0
	s_mov_b32 m0, s58
	v_lshl_add_u64 v[232:233], s[54:55], 0, v[146:147]
	ds_read_b128 v[196:199], v156 offset:32768
	ds_read_b128 v[200:203], v156 offset:33792
	ds_read_b128 v[204:207], v156 offset:34816
	ds_read_b128 v[208:211], v156 offset:35840
	ds_read_b128 v[212:215], v156 offset:36864
	ds_read_b128 v[216:219], v156 offset:37888
	ds_read_b128 v[224:227], v156 offset:38912
	ds_read_b128 v[228:231], v156 offset:39936
	global_load_lds_dwordx4 v[232:233], off
	v_lshl_add_u64 v[232:233], s[54:55], 0, v[144:145]
	s_mov_b32 m0, s59
	s_nop 0
	global_load_lds_dwordx4 v[232:233], off
	s_waitcnt lgkmcnt(8)
	s_barrier
; #define PG8_STAGE(bufoff, gbase, voff) do { _Pragma("unroll") for (int _i = 0; _i < 2; ++_i) \
;         __builtin_amdgcn_global_load_lds((const unsigned*)((const char*)(gbase) + (voff)[_i]), (LAS unsigned*)(lds + (bufoff) + ldsw + _i * 8192), 16, 0, 0); } while (0)
; #define PG8_LDA(dst, b, h) do { _Pragma("unroll") for (int m = 0; m < 4; ++m) _Pragma("unroll") for (int k = 0; k < 2; ++k) dst[m][k] = *(const LAS bf16x8*)(lds + PG8_SA(b, h) + aoff + m * 2048 + k * 1024); } while (0)
; #define PG8_LDB(dst, b, h) do { _Pragma("unroll") for (int n = 0; n < 2; ++n) _Pragma("unroll") for (int k = 0; k < 2; ++k) dst[n][k] = *(const LAS bf16x8*)(lds + PG8_SB(b, h) + boff + n * 2048 + k * 1024); } while (0)
; #define PG8_MMA(ai, bj, At, Bt) do { __builtin_amdgcn_s_setprio(1); _Pragma("unroll") for (int m = 0; m < 4; ++m) _Pragma("unroll") for (int n = 0; n < 2; ++n) _Pragma("unroll") for (int k = 0; k < 2; ++k) \
;         acc[ai][bj][m][n] = __builtin_amdgcn_mfma_f32_16x16x32_bf16(Bt[n][k], At[m][k], acc[ai][bj][m][n], 0, 0, 0); __builtin_amdgcn_s_setprio(0); } while (0)
; #define PG8_WAIT_V(n) asm volatile("s_waitcnt vmcnt(" #n ")" ::: "memory")
; #define PG8_WAIT_L(n) asm volatile("s_waitcnt lgkmcnt(" #n ")" ::: "memory")
; #define PG8_BAR __builtin_amdgcn_s_barrier()
; #define PG8_SCHED __builtin_amdgcn_sched_barrier(0)
; DI void gemm_phase(LAS unsigned char* lds, const Gemm g, const StaticOrder& S, const EpiBf16& E) {
;     ...
;             PG8_WAIT_L(8); PG8_BAR; PG8_WAIT_L(0); PG8_MMA(0, 0, At, B0); PG8_BAR; PG8_SCHED;
;             PG8_LDB(B1, 1, 1); PG8_STAGE(PG8_SB(1, 0), b3, voffB);
;             PG8_BAR; PG8_WAIT_L(0); PG8_MMA(0, 1, At, B1); PG8_BAR;
;             PG8_LDA(At, 1, 1); PG8_STAGE(PG8_SA(1, 0), a3, voffA);
;             PG8_BAR; PG8_WAIT_L(0); PG8_MMA(1, 0, At, B0); PG8_BAR; PG8_SCHED;
;             PG8_STAGE(PG8_SB(1, 1), b3 + hstep, voffB);
;             PG8_WAIT_V(6); PG8_BAR; PG8_MMA(1, 1, At, B1); PG8_BAR;
	s_waitcnt lgkmcnt(0)
	s_setprio 1
	s_waitcnt lgkmcnt(0)
	v_mfma_f32_16x16x32_bf16 v[124:127], v[160:163], v[196:199], v[124:127]
	v_mfma_f32_16x16x32_bf16 v[120:123], v[188:191], v[196:199], v[120:123]
	v_mfma_f32_16x16x32_bf16 v[116:119], v[160:163], v[204:207], v[116:119]
	v_mfma_f32_16x16x32_bf16 v[112:115], v[188:191], v[204:207], v[112:115]
	v_mfma_f32_16x16x32_bf16 v[100:103], v[160:163], v[212:215], v[100:103]
	v_mfma_f32_16x16x32_bf16 v[96:99], v[188:191], v[212:215], v[96:99]
	v_mfma_f32_16x16x32_bf16 v[84:87], v[160:163], v[224:227], v[84:87]
	v_mfma_f32_16x16x32_bf16 v[80:83], v[188:191], v[224:227], v[80:83]
	v_mfma_f32_16x16x32_bf16 v[124:127], v[184:187], v[200:203], v[124:127]
	v_mfma_f32_16x16x32_bf16 v[120:123], v[192:195], v[200:203], v[120:123]
	v_mfma_f32_16x16x32_bf16 v[116:119], v[184:187], v[208:211], v[116:119]
	v_mfma_f32_16x16x32_bf16 v[112:115], v[192:195], v[208:211], v[112:115]
	v_mfma_f32_16x16x32_bf16 v[100:103], v[184:187], v[216:219], v[100:103]
	v_mfma_f32_16x16x32_bf16 v[96:99], v[192:195], v[216:219], v[96:99]
	v_mfma_f32_16x16x32_bf16 v[84:87], v[184:187], v[228:231], v[84:87]
	v_mfma_f32_16x16x32_bf16 v[80:83], v[192:195], v[228:231], v[80:83]
	s_setprio 0
	s_barrier
	s_mov_b32 m0, s60
	v_add_u32_e32 v159, s64, v153
	v_lshl_add_u64 v[164:165], v[164:165], 0, s[34:35]
	ds_read_b128 v[232:235], v159
	ds_read_b128 v[236:239], v159 offset:1024
	ds_read_b128 v[240:243], v159 offset:2048
	ds_read_b128 v[244:247], v159 offset:3072
	global_load_lds_dwordx4 v[164:165], off
	v_lshl_add_u64 v[164:165], v[248:249], 0, s[34:35]
	s_mov_b32 m0, s61
	s_nop 0
	global_load_lds_dwordx4 v[164:165], off
	s_barrier
	s_waitcnt lgkmcnt(0)
	s_setprio 1
	s_waitcnt lgkmcnt(0)
	v_mfma_f32_16x16x32_bf16 v[108:111], v[232:235], v[196:199], v[108:111]
	v_mfma_f32_16x16x32_bf16 v[104:107], v[240:243], v[196:199], v[104:107]
	v_mfma_f32_16x16x32_bf16 v[92:95], v[232:235], v[204:207], v[92:95]
	v_mfma_f32_16x16x32_bf16 v[88:91], v[240:243], v[204:207], v[88:91]
	v_mfma_f32_16x16x32_bf16 v[76:79], v[232:235], v[212:215], v[76:79]
	v_mfma_f32_16x16x32_bf16 v[72:75], v[240:243], v[212:215], v[72:75]
	v_mfma_f32_16x16x32_bf16 v[68:71], v[232:235], v[224:227], v[68:71]
	v_mfma_f32_16x16x32_bf16 v[64:67], v[240:243], v[224:227], v[64:67]
	v_mfma_f32_16x16x32_bf16 v[108:111], v[236:239], v[200:203], v[108:111]
	v_mfma_f32_16x16x32_bf16 v[104:107], v[244:247], v[200:203], v[104:107]
	v_mfma_f32_16x16x32_bf16 v[92:95], v[236:239], v[208:211], v[92:95]
	v_mfma_f32_16x16x32_bf16 v[88:91], v[244:247], v[208:211], v[88:91]
	v_mfma_f32_16x16x32_bf16 v[76:79], v[236:239], v[216:219], v[76:79]
	v_mfma_f32_16x16x32_bf16 v[72:75], v[244:247], v[216:219], v[72:75]
	v_mfma_f32_16x16x32_bf16 v[68:71], v[236:239], v[228:231], v[68:71]
	v_mfma_f32_16x16x32_bf16 v[64:67], v[244:247], v[228:231], v[64:67]
	s_setprio 0
	s_mov_b32 m0, s62
	v_lshl_add_u64 v[164:165], v[250:251], 0, s[34:35]
	s_barrier
	ds_read_b128 v[196:199], v156 offset:49152
	ds_read_b128 v[200:203], v156 offset:50176
	ds_read_b128 v[204:207], v156 offset:51200
	ds_read_b128 v[208:211], v156 offset:52224
	ds_read_b128 v[212:215], v156 offset:53248
	ds_read_b128 v[216:219], v156 offset:54272
	ds_read_b128 v[224:227], v156 offset:55296
	ds_read_b128 v[228:231], v156 offset:56320
	global_load_lds_dwordx4 v[164:165], off
	v_lshl_add_u64 v[134:135], v[134:135], 0, s[34:35]
	s_mov_b32 m0, s63
	s_nop 0
	global_load_lds_dwordx4 v[134:135], off
	s_barrier
	s_waitcnt lgkmcnt(0)
	s_setprio 1
	s_waitcnt lgkmcnt(0)
	v_mfma_f32_16x16x32_bf16 v[60:63], v[160:163], v[196:199], v[60:63]
	v_mfma_f32_16x16x32_bf16 v[56:59], v[188:191], v[196:199], v[56:59]
	v_mfma_f32_16x16x32_bf16 v[52:55], v[160:163], v[204:207], v[52:55]
	v_mfma_f32_16x16x32_bf16 v[48:51], v[188:191], v[204:207], v[48:51]
	v_mfma_f32_16x16x32_bf16 v[36:39], v[160:163], v[212:215], v[36:39]
	v_mfma_f32_16x16x32_bf16 v[32:35], v[188:191], v[212:215], v[32:35]
	v_mfma_f32_16x16x32_bf16 v[20:23], v[160:163], v[224:227], v[20:23]
	v_mfma_f32_16x16x32_bf16 v[16:19], v[188:191], v[224:227], v[16:19]
	v_mfma_f32_16x16x32_bf16 v[60:63], v[184:187], v[200:203], v[60:63]
	v_mfma_f32_16x16x32_bf16 v[56:59], v[192:195], v[200:203], v[56:59]
	v_mfma_f32_16x16x32_bf16 v[52:55], v[184:187], v[208:211], v[52:55]
	v_mfma_f32_16x16x32_bf16 v[48:51], v[192:195], v[208:211], v[48:51]
	v_mfma_f32_16x16x32_bf16 v[36:39], v[184:187], v[216:219], v[36:39]
	v_mfma_f32_16x16x32_bf16 v[32:35], v[192:195], v[216:219], v[32:35]
	v_mfma_f32_16x16x32_bf16 v[20:23], v[184:187], v[228:231], v[20:23]
	v_mfma_f32_16x16x32_bf16 v[16:19], v[192:195], v[228:231], v[16:19]
	s_setprio 0
	s_barrier
	s_add_u32 s52, s52, 0x80080
	s_addc_u32 s53, s53, 0
	s_mov_b32 m0, s65
	v_lshl_add_u64 v[134:135], s[52:53], 0, v[132:133]
	global_load_lds_dwordx4 v[134:135], off
	v_lshl_add_u64 v[134:135], s[52:53], 0, v[142:143]
	s_mov_b32 m0, s66
	s_nop 0
	global_load_lds_dwordx4 v[134:135], off
	s_waitcnt vmcnt(6)
	s_barrier
	s_setprio 1
	v_mfma_f32_16x16x32_bf16 v[44:47], v[232:235], v[196:199], v[44:47]
	v_mfma_f32_16x16x32_bf16 v[40:43], v[240:243], v[196:199], v[40:43]
	v_mfma_f32_16x16x32_bf16 v[28:31], v[232:235], v[204:207], v[28:31]
	v_mfma_f32_16x16x32_bf16 v[24:27], v[240:243], v[204:207], v[24:27]
	v_mfma_f32_16x16x32_bf16 v[12:15], v[232:235], v[212:215], v[12:15]
	v_mfma_f32_16x16x32_bf16 v[8:11], v[240:243], v[212:215], v[8:11]
	v_mfma_f32_16x16x32_bf16 v[4:7], v[232:235], v[224:227], v[4:7]
	v_mfma_f32_16x16x32_bf16 v[0:3], v[240:243], v[224:227], v[0:3]
	v_mfma_f32_16x16x32_bf16 v[44:47], v[236:239], v[200:203], v[44:47]
	v_mfma_f32_16x16x32_bf16 v[40:43], v[244:247], v[200:203], v[40:43]
	v_mfma_f32_16x16x32_bf16 v[28:31], v[236:239], v[208:211], v[28:31]
	v_mfma_f32_16x16x32_bf16 v[24:27], v[244:247], v[208:211], v[24:27]
	v_mfma_f32_16x16x32_bf16 v[12:15], v[236:239], v[216:219], v[12:15]
	v_mfma_f32_16x16x32_bf16 v[8:11], v[244:247], v[216:219], v[8:11]
	v_mfma_f32_16x16x32_bf16 v[4:7], v[236:239], v[228:231], v[4:7]
	v_mfma_f32_16x16x32_bf16 v[0:3], v[244:247], v[228:231], v[0:3]
	s_setprio 0
	s_add_i32 s73, s73, 2
	s_add_u32 s50, s50, 0x100
	s_addc_u32 s51, s51, 0
	s_add_u32 s71, s71, 0x100
	s_addc_u32 s72, s72, 0
	s_cmp_gt_u32 s73, 29
	s_barrier
	s_cbranch_scc0 .LBB0_181
	s_branch .Lg1_after
; #define PG8_STAGE(bufoff, gbase, voff) do { _Pragma("unroll") for (int _i = 0; _i < 2; ++_i) \
;         __builtin_amdgcn_global_load_lds((const unsigned*)((const char*)(gbase) + (voff)[_i]), (LAS unsigned*)(lds + (bufoff) + ldsw + _i * 8192), 16, 0, 0); } while (0)
; #define PG8_LDA(dst, b, h) do { _Pragma("unroll") for (int m = 0; m < 4; ++m) _Pragma("unroll") for (int k = 0; k < 2; ++k) dst[m][k] = *(const LAS bf16x8*)(lds + PG8_SA(b, h) + aoff + m * 2048 + k * 1024); } while (0)
; #define PG8_LDB(dst, b, h) do { _Pragma("unroll") for (int n = 0; n < 2; ++n) _Pragma("unroll") for (int k = 0; k < 2; ++k) dst[n][k] = *(const LAS bf16x8*)(lds + PG8_SB(b, h) + boff + n * 2048 + k * 1024); } while (0)
; #define PG8_MMA(ai, bj, At, Bt) do { __builtin_amdgcn_s_setprio(1); _Pragma("unroll") for (int m = 0; m < 4; ++m) _Pragma("unroll") for (int n = 0; n < 2; ++n) _Pragma("unroll") for (int k = 0; k < 2; ++k) \
;         acc[ai][bj][m][n] = __builtin_amdgcn_mfma_f32_16x16x32_bf16(Bt[n][k], At[m][k], acc[ai][bj][m][n], 0, 0, 0); __builtin_amdgcn_s_setprio(0); } while (0)
; #define PG8_WAIT_L(n) asm volatile("s_waitcnt lgkmcnt(" #n ")" ::: "memory")
; #define PG8_BAR __builtin_amdgcn_s_barrier()
; #define PG8_SCHED __builtin_amdgcn_sched_barrier(0)
; DI void gemm_phase(LAS unsigned char* lds, const Gemm g, const StaticOrder& S, const EpiBf16& E) {
;     ...
;         for (int t = 0; t < nt; t += 2) {
;             const bool last = (t == nt - 2);
;             const char* a1 = cA + (size_t)(t + 1) * kstep;
;             const char* a2 = last ? nA : cA + (size_t)(t + 2) * kstep; const char* b2 = last ? nB : cB + (size_t)(t + 2) * kstep;
;             const char* a3 = a2 + kstep; const char* b3 = b2 + kstep;
;             PG8_LDB(B0, 0, 0); PG8_SCHED; PG8_LDA(At, 0, 0); PG8_STAGE(PG8_SA(1, 1), a1 + hstep, voffA);
;             PG8_WAIT_L(8); PG8_BAR; PG8_WAIT_L(0); PG8_MMA(0, 0, At, B0); PG8_BAR; PG8_SCHED;
;             PG8_LDB(B1, 0, 1); PG8_STAGE(PG8_SB(0, 0), b2, voffB);
;             PG8_BAR; PG8_WAIT_L(0); PG8_MMA(0, 1, At, B1); PG8_BAR;
;             PG8_LDA(At, 0, 1); PG8_STAGE(PG8_SA(0, 0), a2, voffA);
;             PG8_BAR; PG8_WAIT_L(0); PG8_MMA(1, 0, At, B0); PG8_BAR; PG8_SCHED;
.Lg1_young:
	ds_read_b128 v[160:163], v155
	ds_read_b128 v[184:187], v155 offset:1024
	ds_read_b128 v[188:191], v155 offset:2048
	ds_read_b128 v[192:195], v155 offset:3072
	s_add_u32 s4, s50, 0xfff80080
	s_addc_u32 s5, s51, -1
	s_cmp_eq_u32 s73, 28
	s_cselect_b32 s55, s45, s5
	s_cselect_b32 s54, s69, s4
	s_cselect_b32 s53, s43, s72
	s_cselect_b32 s52, s70, s71
	v_lshl_add_u64 v[164:165], s[50:51], 0, v[148:149]
	s_add_i32 m0, s31, 0xc000
	ds_read_b128 v[196:199], v156
	ds_read_b128 v[200:203], v156 offset:1024
	ds_read_b128 v[204:207], v156 offset:2048
	ds_read_b128 v[208:211], v156 offset:3072
	ds_read_b128 v[212:215], v156 offset:4096
	ds_read_b128 v[216:219], v156 offset:5120
	ds_read_b128 v[224:227], v156 offset:6144
	ds_read_b128 v[228:231], v156 offset:7168
	global_load_lds_dwordx4 v[164:165], off
	v_lshl_add_u64 v[164:165], s[50:51], 0, v[150:151]
	s_add_i32 m0, s31, 0xe000
	s_nop 0
	global_load_lds_dwordx4 v[164:165], off
	s_waitcnt lgkmcnt(8)
	s_barrier
	s_waitcnt lgkmcnt(0)
	s_setprio 2
	s_waitcnt lgkmcnt(0)
	v_mfma_f32_16x16x32_bf16 v[124:127], v[160:163], v[196:199], v[124:127]
	v_mfma_f32_16x16x32_bf16 v[120:123], v[188:191], v[196:199], v[120:123]
	v_mfma_f32_16x16x32_bf16 v[116:119], v[160:163], v[204:207], v[116:119]
	v_mfma_f32_16x16x32_bf16 v[112:115], v[188:191], v[204:207], v[112:115]
	v_mfma_f32_16x16x32_bf16 v[100:103], v[160:163], v[212:215], v[100:103]
	v_mfma_f32_16x16x32_bf16 v[96:99], v[188:191], v[212:215], v[96:99]
	v_mfma_f32_16x16x32_bf16 v[84:87], v[160:163], v[224:227], v[84:87]
	v_mfma_f32_16x16x32_bf16 v[80:83], v[188:191], v[224:227], v[80:83]
	v_mfma_f32_16x16x32_bf16 v[124:127], v[184:187], v[200:203], v[124:127]
	v_mfma_f32_16x16x32_bf16 v[120:123], v[192:195], v[200:203], v[120:123]
	v_mfma_f32_16x16x32_bf16 v[116:119], v[184:187], v[208:211], v[116:119]
	v_mfma_f32_16x16x32_bf16 v[112:115], v[192:195], v[208:211], v[112:115]
	v_mfma_f32_16x16x32_bf16 v[100:103], v[184:187], v[216:219], v[100:103]
	v_mfma_f32_16x16x32_bf16 v[96:99], v[192:195], v[216:219], v[96:99]
	v_mfma_f32_16x16x32_bf16 v[84:87], v[184:187], v[228:231], v[84:87]
	v_mfma_f32_16x16x32_bf16 v[80:83], v[192:195], v[228:231], v[80:83]
	s_setprio 1
	s_barrier
	s_mov_b32 m0, s28
	v_lshl_add_u64 v[164:165], s[52:53], 0, v[132:133]
	ds_read_b128 v[232:235], v157
	ds_read_b128 v[236:239], v157 offset:1024
	ds_read_b128 v[240:243], v157 offset:2048
	ds_read_b128 v[244:247], v157 offset:3072
	global_load_lds_dwordx4 v[164:165], off
	v_lshl_add_u64 v[248:249], s[52:53], 0, v[142:143]
	s_mov_b32 m0, s30
	s_nop 0
	global_load_lds_dwordx4 v[248:249], off
	s_barrier
	s_waitcnt lgkmcnt(0)
	s_setprio 2
	s_waitcnt lgkmcnt(0)
	v_mfma_f32_16x16x32_bf16 v[108:111], v[232:235], v[196:199], v[108:111]
	v_mfma_f32_16x16x32_bf16 v[104:107], v[240:243], v[196:199], v[104:107]
	v_mfma_f32_16x16x32_bf16 v[92:95], v[232:235], v[204:207], v[92:95]
	v_mfma_f32_16x16x32_bf16 v[88:91], v[240:243], v[204:207], v[88:91]
	v_mfma_f32_16x16x32_bf16 v[76:79], v[232:235], v[212:215], v[76:79]
	v_mfma_f32_16x16x32_bf16 v[72:75], v[240:243], v[212:215], v[72:75]
	v_mfma_f32_16x16x32_bf16 v[68:71], v[232:235], v[224:227], v[68:71]
	v_mfma_f32_16x16x32_bf16 v[64:67], v[240:243], v[224:227], v[64:67]
	v_mfma_f32_16x16x32_bf16 v[108:111], v[236:239], v[200:203], v[108:111]
	v_mfma_f32_16x16x32_bf16 v[104:107], v[244:247], v[200:203], v[104:107]
	v_mfma_f32_16x16x32_bf16 v[92:95], v[236:239], v[208:211], v[92:95]
	v_mfma_f32_16x16x32_bf16 v[88:91], v[244:247], v[208:211], v[88:91]
	v_mfma_f32_16x16x32_bf16 v[76:79], v[236:239], v[216:219], v[76:79]
	v_mfma_f32_16x16x32_bf16 v[72:75], v[244:247], v[216:219], v[72:75]
	v_mfma_f32_16x16x32_bf16 v[68:71], v[236:239], v[228:231], v[68:71]
	v_mfma_f32_16x16x32_bf16 v[64:67], v[244:247], v[228:231], v[64:67]
	s_setprio 1
	s_mov_b32 m0, s31
	v_lshl_add_u64 v[250:251], s[54:55], 0, v[146:147]
	s_barrier
	ds_read_b128 v[196:199], v156 offset:16384
	ds_read_b128 v[200:203], v156 offset:17408
	ds_read_b128 v[204:207], v156 offset:18432
	ds_read_b128 v[208:211], v156 offset:19456
	ds_read_b128 v[212:215], v156 offset:20480
	ds_read_b128 v[216:219], v156 offset:21504
	ds_read_b128 v[224:227], v156 offset:22528
	ds_read_b128 v[228:231], v156 offset:23552
	global_load_lds_dwordx4 v[250:251], off
	v_lshl_add_u64 v[134:135], s[54:55], 0, v[144:145]
	s_mov_b32 m0, s41
	s_nop 0
	global_load_lds_dwordx4 v[134:135], off
	s_barrier
	s_waitcnt lgkmcnt(0)
	s_setprio 2
	s_waitcnt lgkmcnt(0)
	v_mfma_f32_16x16x32_bf16 v[60:63], v[160:163], v[196:199], v[60:63]
	v_mfma_f32_16x16x32_bf16 v[56:59], v[188:191], v[196:199], v[56:59]
	v_mfma_f32_16x16x32_bf16 v[52:55], v[160:163], v[204:207], v[52:55]
	v_mfma_f32_16x16x32_bf16 v[48:51], v[188:191], v[204:207], v[48:51]
	v_mfma_f32_16x16x32_bf16 v[36:39], v[160:163], v[212:215], v[36:39]
	v_mfma_f32_16x16x32_bf16 v[32:35], v[188:191], v[212:215], v[32:35]
	v_mfma_f32_16x16x32_bf16 v[20:23], v[160:163], v[224:227], v[20:23]
	v_mfma_f32_16x16x32_bf16 v[16:19], v[188:191], v[224:227], v[16:19]
	v_mfma_f32_16x16x32_bf16 v[60:63], v[184:187], v[200:203], v[60:63]
	v_mfma_f32_16x16x32_bf16 v[56:59], v[192:195], v[200:203], v[56:59]
	v_mfma_f32_16x16x32_bf16 v[52:55], v[184:187], v[208:211], v[52:55]
	v_mfma_f32_16x16x32_bf16 v[48:51], v[192:195], v[208:211], v[48:51]
	v_mfma_f32_16x16x32_bf16 v[36:39], v[184:187], v[216:219], v[36:39]
	v_mfma_f32_16x16x32_bf16 v[32:35], v[192:195], v[216:219], v[32:35]
	v_mfma_f32_16x16x32_bf16 v[20:23], v[184:187], v[228:231], v[20:23]
	v_mfma_f32_16x16x32_bf16 v[16:19], v[192:195], v[228:231], v[16:19]
	s_setprio 1
	s_barrier
; #define PG8_STAGE(bufoff, gbase, voff) do { _Pragma("unroll") for (int _i = 0; _i < 2; ++_i) \
;         __builtin_amdgcn_global_load_lds((const unsigned*)((const char*)(gbase) + (voff)[_i]), (LAS unsigned*)(lds + (bufoff) + ldsw + _i * 8192), 16, 0, 0); } while (0)
; #define PG8_LDA(dst, b, h) do { _Pragma("unroll") for (int m = 0; m < 4; ++m) _Pragma("unroll") for (int k = 0; k < 2; ++k) dst[m][k] = *(const LAS bf16x8*)(lds + PG8_SA(b, h) + aoff + m * 2048 + k * 1024); } while (0)
; #define PG8_LDB(dst, b, h) do { _Pragma("unroll") for (int n = 0; n < 2; ++n) _Pragma("unroll") for (int k = 0; k < 2; ++k) dst[n][k] = *(const LAS bf16x8*)(lds + PG8_SB(b, h) + boff + n * 2048 + k * 1024); } while (0)
; #define PG8_MMA(ai, bj, At, Bt) do { __builtin_amdgcn_s_setprio(1); _Pragma("unroll") for (int m = 0; m < 4; ++m) _Pragma("unroll") for (int n = 0; n < 2; ++n) _Pragma("unroll") for (int k = 0; k < 2; ++k) \
;         acc[ai][bj][m][n] = __builtin_amdgcn_mfma_f32_16x16x32_bf16(Bt[n][k], At[m][k], acc[ai][bj][m][n], 0, 0, 0); __builtin_amdgcn_s_setprio(0); } while (0)
; #define PG8_WAIT_V(n) asm volatile("s_waitcnt vmcnt(" #n ")" ::: "memory")
; #define PG8_WAIT_L(n) asm volatile("s_waitcnt lgkmcnt(" #n ")" ::: "memory")
; #define PG8_BAR __builtin_amdgcn_s_barrier()
; #define PG8_SCHED __builtin_amdgcn_sched_barrier(0)
; DI void gemm_phase(LAS unsigned char* lds, const Gemm g, const StaticOrder& S, const EpiBf16& E) {
;     ...
;             PG8_STAGE(PG8_SB(0, 1), b2 + hstep, voffB);
;             PG8_WAIT_V(6); PG8_BAR; PG8_MMA(1, 1, At, B1); PG8_BAR;
;             PG8_LDB(B0, 1, 0); PG8_SCHED; PG8_LDA(At, 1, 0); PG8_STAGE(PG8_SA(0, 1), a2 + hstep, voffA);
;             PG8_WAIT_L(8); PG8_BAR; PG8_WAIT_L(0); PG8_MMA(0, 0, At, B0); PG8_BAR; PG8_SCHED;
;             PG8_LDB(B1, 1, 1); PG8_STAGE(PG8_SB(1, 0), b3, voffB);
;             PG8_BAR; PG8_WAIT_L(0); PG8_MMA(0, 1, At, B1); PG8_BAR;
;             PG8_LDA(At, 1, 1); PG8_STAGE(PG8_SA(1, 0), a3, voffA);
	s_add_u32 s74, s52, 0x80000
	s_addc_u32 s75, s53, 0
	s_mov_b32 m0, s56
	v_lshl_add_u64 v[160:161], s[74:75], 0, v[132:133]
	global_load_lds_dwordx4 v[160:161], off
	v_lshl_add_u64 v[160:161], s[74:75], 0, v[142:143]
	s_mov_b32 m0, s57
	s_nop 0
	global_load_lds_dwordx4 v[160:161], off
	s_waitcnt vmcnt(6)
	s_barrier
	s_setprio 2
	v_mfma_f32_16x16x32_bf16 v[44:47], v[232:235], v[196:199], v[44:47]
	v_mfma_f32_16x16x32_bf16 v[40:43], v[240:243], v[196:199], v[40:43]
	v_mfma_f32_16x16x32_bf16 v[28:31], v[232:235], v[204:207], v[28:31]
	v_mfma_f32_16x16x32_bf16 v[24:27], v[240:243], v[204:207], v[24:27]
	v_mfma_f32_16x16x32_bf16 v[12:15], v[232:235], v[212:215], v[12:15]
	v_mfma_f32_16x16x32_bf16 v[8:11], v[240:243], v[212:215], v[8:11]
	v_mfma_f32_16x16x32_bf16 v[4:7], v[232:235], v[224:227], v[4:7]
	v_mfma_f32_16x16x32_bf16 v[0:3], v[240:243], v[224:227], v[0:3]
	v_mfma_f32_16x16x32_bf16 v[44:47], v[236:239], v[200:203], v[44:47]
	v_mfma_f32_16x16x32_bf16 v[40:43], v[244:247], v[200:203], v[40:43]
	v_mfma_f32_16x16x32_bf16 v[28:31], v[236:239], v[208:211], v[28:31]
	v_mfma_f32_16x16x32_bf16 v[24:27], v[244:247], v[208:211], v[24:27]
	v_mfma_f32_16x16x32_bf16 v[12:15], v[236:239], v[216:219], v[12:15]
	v_mfma_f32_16x16x32_bf16 v[8:11], v[244:247], v[216:219], v[8:11]
	v_mfma_f32_16x16x32_bf16 v[4:7], v[236:239], v[228:231], v[4:7]
	v_mfma_f32_16x16x32_bf16 v[0:3], v[244:247], v[228:231], v[0:3]
	s_setprio 1
	s_barrier
	ds_read_b128 v[160:163], v158
	ds_read_b128 v[184:187], v158 offset:1024
	ds_read_b128 v[188:191], v158 offset:2048
	ds_read_b128 v[192:195], v158 offset:3072
	s_add_u32 s54, s54, 0x80000
	s_addc_u32 s55, s55, 0
	s_mov_b32 m0, s58
	v_lshl_add_u64 v[232:233], s[54:55], 0, v[146:147]
	ds_read_b128 v[196:199], v156 offset:32768
	ds_read_b128 v[200:203], v156 offset:33792
	ds_read_b128 v[204:207], v156 offset:34816
	ds_read_b128 v[208:211], v156 offset:35840
	ds_read_b128 v[212:215], v156 offset:36864
	ds_read_b128 v[216:219], v156 offset:37888
	ds_read_b128 v[224:227], v156 offset:38912
	ds_read_b128 v[228:231], v156 offset:39936
	global_load_lds_dwordx4 v[232:233], off
	v_lshl_add_u64 v[232:233], s[54:55], 0, v[144:145]
	s_mov_b32 m0, s59
	s_nop 0
	global_load_lds_dwordx4 v[232:233], off
	s_waitcnt lgkmcnt(8)
	s_barrier
	s_waitcnt lgkmcnt(0)
	s_setprio 2
	s_waitcnt lgkmcnt(0)
	v_mfma_f32_16x16x32_bf16 v[124:127], v[160:163], v[196:199], v[124:127]
	v_mfma_f32_16x16x32_bf16 v[120:123], v[188:191], v[196:199], v[120:123]
	v_mfma_f32_16x16x32_bf16 v[116:119], v[160:163], v[204:207], v[116:119]
	v_mfma_f32_16x16x32_bf16 v[112:115], v[188:191], v[204:207], v[112:115]
	v_mfma_f32_16x16x32_bf16 v[100:103], v[160:163], v[212:215], v[100:103]
	v_mfma_f32_16x16x32_bf16 v[96:99], v[188:191], v[212:215], v[96:99]
	v_mfma_f32_16x16x32_bf16 v[84:87], v[160:163], v[224:227], v[84:87]
	v_mfma_f32_16x16x32_bf16 v[80:83], v[188:191], v[224:227], v[80:83]
	v_mfma_f32_16x16x32_bf16 v[124:127], v[184:187], v[200:203], v[124:127]
	v_mfma_f32_16x16x32_bf16 v[120:123], v[192:195], v[200:203], v[120:123]
	v_mfma_f32_16x16x32_bf16 v[116:119], v[184:187], v[208:211], v[116:119]
	v_mfma_f32_16x16x32_bf16 v[112:115], v[192:195], v[208:211], v[112:115]
	v_mfma_f32_16x16x32_bf16 v[100:103], v[184:187], v[216:219], v[100:103]
	v_mfma_f32_16x16x32_bf16 v[96:99], v[192:195], v[216:219], v[96:99]
	v_mfma_f32_16x16x32_bf16 v[84:87], v[184:187], v[228:231], v[84:87]
	v_mfma_f32_16x16x32_bf16 v[80:83], v[192:195], v[228:231], v[80:83]
	s_setprio 1
	s_barrier
	s_mov_b32 m0, s60
	v_add_u32_e32 v159, s64, v153
	v_lshl_add_u64 v[164:165], v[164:165], 0, s[34:35]
	ds_read_b128 v[232:235], v159
	ds_read_b128 v[236:239], v159 offset:1024
	ds_read_b128 v[240:243], v159 offset:2048
	ds_read_b128 v[244:247], v159 offset:3072
	global_load_lds_dwordx4 v[164:165], off
	v_lshl_add_u64 v[164:165], v[248:249], 0, s[34:35]
	s_mov_b32 m0, s61
	s_nop 0
	global_load_lds_dwordx4 v[164:165], off
	s_barrier
	s_waitcnt lgkmcnt(0)
	s_setprio 2
	s_waitcnt lgkmcnt(0)
	v_mfma_f32_16x16x32_bf16 v[108:111], v[232:235], v[196:199], v[108:111]
	v_mfma_f32_16x16x32_bf16 v[104:107], v[240:243], v[196:199], v[104:107]
	v_mfma_f32_16x16x32_bf16 v[92:95], v[232:235], v[204:207], v[92:95]
	v_mfma_f32_16x16x32_bf16 v[88:91], v[240:243], v[204:207], v[88:91]
	v_mfma_f32_16x16x32_bf16 v[76:79], v[232:235], v[212:215], v[76:79]
	v_mfma_f32_16x16x32_bf16 v[72:75], v[240:243], v[212:215], v[72:75]
	v_mfma_f32_16x16x32_bf16 v[68:71], v[232:235], v[224:227], v[68:71]
	v_mfma_f32_16x16x32_bf16 v[64:67], v[240:243], v[224:227], v[64:67]
	v_mfma_f32_16x16x32_bf16 v[108:111], v[236:239], v[200:203], v[108:111]
	v_mfma_f32_16x16x32_bf16 v[104:107], v[244:247], v[200:203], v[104:107]
	v_mfma_f32_16x16x32_bf16 v[92:95], v[236:239], v[208:211], v[92:95]
	v_mfma_f32_16x16x32_bf16 v[88:91], v[244:247], v[208:211], v[88:91]
	v_mfma_f32_16x16x32_bf16 v[76:79], v[236:239], v[216:219], v[76:79]
	v_mfma_f32_16x16x32_bf16 v[72:75], v[244:247], v[216:219], v[72:75]
	v_mfma_f32_16x16x32_bf16 v[68:71], v[236:239], v[228:231], v[68:71]
	v_mfma_f32_16x16x32_bf16 v[64:67], v[244:247], v[228:231], v[64:67]
	s_setprio 1
	s_mov_b32 m0, s62
	v_lshl_add_u64 v[164:165], v[250:251], 0, s[34:35]
	s_barrier
	ds_read_b128 v[196:199], v156 offset:49152
	ds_read_b128 v[200:203], v156 offset:50176
	ds_read_b128 v[204:207], v156 offset:51200
	ds_read_b128 v[208:211], v156 offset:52224
	ds_read_b128 v[212:215], v156 offset:53248
	ds_read_b128 v[216:219], v156 offset:54272
	ds_read_b128 v[224:227], v156 offset:55296
	ds_read_b128 v[228:231], v156 offset:56320
	global_load_lds_dwordx4 v[164:165], off
	v_lshl_add_u64 v[134:135], v[134:135], 0, s[34:35]
	s_mov_b32 m0, s63
	s_nop 0
	global_load_lds_dwordx4 v[134:135], off
	s_barrier
; #define PG8_STAGE(bufoff, gbase, voff) do { _Pragma("unroll") for (int _i = 0; _i < 2; ++_i) \
;         __builtin_amdgcn_global_load_lds((const unsigned*)((const char*)(gbase) + (voff)[_i]), (LAS unsigned*)(lds + (bufoff) + ldsw + _i * 8192), 16, 0, 0); } while (0)
; #define PG8_MMA(ai, bj, At, Bt) do { __builtin_amdgcn_s_setprio(1); _Pragma("unroll") for (int m = 0; m < 4; ++m) _Pragma("unroll") for (int n = 0; n < 2; ++n) _Pragma("unroll") for (int k = 0; k < 2; ++k) \
;         acc[ai][bj][m][n] = __builtin_amdgcn_mfma_f32_16x16x32_bf16(Bt[n][k], At[m][k], acc[ai][bj][m][n], 0, 0, 0); __builtin_amdgcn_s_setprio(0); } while (0)
; #define PG8_WAIT_V(n) asm volatile("s_waitcnt vmcnt(" #n ")" ::: "memory")
; #define PG8_WAIT_L(n) asm volatile("s_waitcnt lgkmcnt(" #n ")" ::: "memory")
; #define PG8_BAR __builtin_amdgcn_s_barrier()
; #define PG8_SCHED __builtin_amdgcn_sched_barrier(0)
; DI void gemm_phase(LAS unsigned char* lds, const Gemm g, const StaticOrder& S, const EpiBf16& E) {
;     ...
;             PG8_BAR; PG8_WAIT_L(0); PG8_MMA(1, 0, At, B0); PG8_BAR; PG8_SCHED;
;             PG8_STAGE(PG8_SB(1, 1), b3 + hstep, voffB);
;             PG8_WAIT_V(6); PG8_BAR; PG8_MMA(1, 1, At, B1); PG8_BAR;
;         }
	s_waitcnt lgkmcnt(0)
	s_setprio 2
	s_waitcnt lgkmcnt(0)
	v_mfma_f32_16x16x32_bf16 v[60:63], v[160:163], v[196:199], v[60:63]
	v_mfma_f32_16x16x32_bf16 v[56:59], v[188:191], v[196:199], v[56:59]
	v_mfma_f32_16x16x32_bf16 v[52:55], v[160:163], v[204:207], v[52:55]
	v_mfma_f32_16x16x32_bf16 v[48:51], v[188:191], v[204:207], v[48:51]
	v_mfma_f32_16x16x32_bf16 v[36:39], v[160:163], v[212:215], v[36:39]
	v_mfma_f32_16x16x32_bf16 v[32:35], v[188:191], v[212:215], v[32:35]
	v_mfma_f32_16x16x32_bf16 v[20:23], v[160:163], v[224:227], v[20:23]
	v_mfma_f32_16x16x32_bf16 v[16:19], v[188:191], v[224:227], v[16:19]
	v_mfma_f32_16x16x32_bf16 v[60:63], v[184:187], v[200:203], v[60:63]
	v_mfma_f32_16x16x32_bf16 v[56:59], v[192:195], v[200:203], v[56:59]
	v_mfma_f32_16x16x32_bf16 v[52:55], v[184:187], v[208:211], v[52:55]
	v_mfma_f32_16x16x32_bf16 v[48:51], v[192:195], v[208:211], v[48:51]
	v_mfma_f32_16x16x32_bf16 v[36:39], v[184:187], v[216:219], v[36:39]
	v_mfma_f32_16x16x32_bf16 v[32:35], v[192:195], v[216:219], v[32:35]
	v_mfma_f32_16x16x32_bf16 v[20:23], v[184:187], v[228:231], v[20:23]
	v_mfma_f32_16x16x32_bf16 v[16:19], v[192:195], v[228:231], v[16:19]
	s_setprio 1
	s_barrier
	s_add_u32 s52, s52, 0x80080
	s_addc_u32 s53, s53, 0
	s_mov_b32 m0, s65
	v_lshl_add_u64 v[134:135], s[52:53], 0, v[132:133]
	global_load_lds_dwordx4 v[134:135], off
	v_lshl_add_u64 v[134:135], s[52:53], 0, v[142:143]
	s_mov_b32 m0, s66
	s_nop 0
	global_load_lds_dwordx4 v[134:135], off
	s_waitcnt vmcnt(6)
	s_barrier
	s_setprio 2
	v_mfma_f32_16x16x32_bf16 v[44:47], v[232:235], v[196:199], v[44:47]
	v_mfma_f32_16x16x32_bf16 v[40:43], v[240:243], v[196:199], v[40:43]
	v_mfma_f32_16x16x32_bf16 v[28:31], v[232:235], v[204:207], v[28:31]
	v_mfma_f32_16x16x32_bf16 v[24:27], v[240:243], v[204:207], v[24:27]
	v_mfma_f32_16x16x32_bf16 v[12:15], v[232:235], v[212:215], v[12:15]
	v_mfma_f32_16x16x32_bf16 v[8:11], v[240:243], v[212:215], v[8:11]
	v_mfma_f32_16x16x32_bf16 v[4:7], v[232:235], v[224:227], v[4:7]
	v_mfma_f32_16x16x32_bf16 v[0:3], v[240:243], v[224:227], v[0:3]
	v_mfma_f32_16x16x32_bf16 v[44:47], v[236:239], v[200:203], v[44:47]
	v_mfma_f32_16x16x32_bf16 v[40:43], v[244:247], v[200:203], v[40:43]
	v_mfma_f32_16x16x32_bf16 v[28:31], v[236:239], v[208:211], v[28:31]
	v_mfma_f32_16x16x32_bf16 v[24:27], v[244:247], v[208:211], v[24:27]
	v_mfma_f32_16x16x32_bf16 v[12:15], v[236:239], v[216:219], v[12:15]
	v_mfma_f32_16x16x32_bf16 v[8:11], v[244:247], v[216:219], v[8:11]
	v_mfma_f32_16x16x32_bf16 v[4:7], v[236:239], v[228:231], v[4:7]
	v_mfma_f32_16x16x32_bf16 v[0:3], v[244:247], v[228:231], v[0:3]
	s_setprio 1
	s_add_i32 s73, s73, 2
	s_add_u32 s50, s50, 0x100
	s_addc_u32 s51, s51, 0
	s_add_u32 s71, s71, 0x100
	s_addc_u32 s72, s72, 0
	s_cmp_gt_u32 s73, 29
	s_barrier
	s_cbranch_scc0 .Lg1_young
	s_setprio 0
; #define PG8_WAIT_V(n) asm volatile("s_waitcnt vmcnt(" #n ")" ::: "memory")
; #define PG8_BAR __builtin_amdgcn_s_barrier()
;     DI void operator()(const f32x4 (&acc)[2][2][4][2], const Unit& u, int wr, int wc, int fr, int fq) const {
;         const int row0 = u.pm * BM + wr * 64 + fr; const int col0 = u.pn * BM + wc * 32 + 8 * fq;
; #pragma unroll
;         for (int ai = 0; ai < 2; ++ai)
; #pragma unroll
;             for (int m = 0; m < 4; ++m) { bf16_t* rowp = O + (size_t)(row0 + ai * HALF + m * 16) * ldc + col0;
; #pragma unroll
;                 for (int bj = 0; bj < 2; ++bj) { const f32x4 v0 = acc[ai][bj][m][0], v1 = acc[ai][bj][m][1];
;                     u32x4 w; w.x = pk2(v0[0], v0[1]); w.y = pk2(v0[2], v0[3]); w.z = pk2(v1[0], v1[1]); w.w = pk2(v1[2], v1[3]);
;                     *(u32x4*)(rowp + bj * HALF) = w; } }
;     }
; DI void gemm_phase(LAS unsigned char* lds, const Gemm g, const StaticOrder& S, const EpiBf16& E) {
;     ...
;         E(acc, cur, wr, wc, fr, fq);
;         if (!has_next) break;
; #pragma unroll
;         for (int a = 0; a < 2; ++a)
; #pragma unroll
;             for (int b = 0; b < 2; ++b)
; #pragma unroll
;                 for (int m = 0; m < 4; ++m)
; #pragma unroll
;                     for (int n = 0; n < 2; ++n) acc[a][b][m][n] = (f32x4){0.f, 0.f, 0.f, 0.f};
;         cur = nxt; cA = nA; cB = nB; ++ui;
;     }
;     PG8_WAIT_V(0);
;     if (wr == 0) PG8_BAR;
;     PG8_BAR;
.Lg1_after:
	v_lshl_add_u32 v134, s40, 8, v152
	v_lshl_or_b32 v160, s68, 8, v154
	v_ashrrev_i32_e32 v161, 31, v160
	v_mov_b64_e32 v[162:163], s[38:39]
	s_movk_i32 s4, 0x3800
	v_cvt_pk_bf16_f32 v68, v68, v69
	v_cvt_pk_bf16_f32 v69, v70, v71
	v_cvt_pk_bf16_f32 v70, v64, v65
	v_add_u32_e32 v64, 0x80, v134
	v_mad_i64_i32 v[164:165], s[50:51], v134, s4, v[162:163]
	v_lshlrev_b64 v[160:161], 1, v[160:161]
	v_cvt_pk_bf16_f32 v108, v108, v109
	v_cvt_pk_bf16_f32 v109, v110, v111
	v_cvt_pk_bf16_f32 v110, v104, v105
	v_or_b32_e32 v104, 16, v134
	v_mad_i64_i32 v[64:65], s[50:51], v64, s4, v[162:163]
	v_cvt_pk_bf16_f32 v44, v44, v45
	v_cvt_pk_bf16_f32 v45, v46, v47
	v_cvt_pk_bf16_f32 v46, v40, v41
	v_add_u32_e32 v40, 0x90, v134
	v_lshl_add_u64 v[164:165], v[164:165], 0, v[160:161]
	v_cvt_pk_bf16_f32 v111, v106, v107
	v_mad_i64_i32 v[104:105], s[50:51], v104, s4, v[162:163]
	v_cvt_pk_bf16_f32 v92, v92, v93
	v_cvt_pk_bf16_f32 v93, v94, v95
	v_cvt_pk_bf16_f32 v94, v88, v89
	v_or_b32_e32 v88, 32, v134
	v_lshl_add_u64 v[64:65], v[64:65], 0, v[160:161]
	v_cvt_pk_bf16_f32 v47, v42, v43
	v_mad_i64_i32 v[40:41], s[50:51], v40, s4, v[162:163]
	v_cvt_pk_bf16_f32 v28, v28, v29
	v_cvt_pk_bf16_f32 v29, v30, v31
	v_cvt_pk_bf16_f32 v30, v24, v25
	v_add_u32_e32 v24, 0xa0, v134
	global_store_dwordx4 v[164:165], v[108:111], off offset:256 sc1
	v_cvt_pk_bf16_f32 v95, v90, v91
	v_mad_i64_i32 v[88:89], s[50:51], v88, s4, v[162:163]
	v_lshl_add_u64 v[108:109], v[104:105], 0, v[160:161]
	v_cvt_pk_bf16_f32 v76, v76, v77
	v_cvt_pk_bf16_f32 v77, v78, v79
	v_cvt_pk_bf16_f32 v78, v72, v73
	v_or_b32_e32 v72, 48, v134
	global_store_dwordx4 v[64:65], v[44:47], off offset:256 sc1
	v_cvt_pk_bf16_f32 v31, v26, v27
	v_mad_i64_i32 v[24:25], s[50:51], v24, s4, v[162:163]
	v_lshl_add_u64 v[44:45], v[40:41], 0, v[160:161]
	v_cvt_pk_bf16_f32 v12, v12, v13
	v_cvt_pk_bf16_f32 v13, v14, v15
	v_cvt_pk_bf16_f32 v14, v8, v9
	v_add_u32_e32 v8, 0xb0, v134
	global_store_dwordx4 v[108:109], v[92:95], off offset:256 sc1
	v_cvt_pk_bf16_f32 v79, v74, v75
	v_mad_i64_i32 v[72:73], s[50:51], v72, s4, v[162:163]
	v_lshl_add_u64 v[92:93], v[88:89], 0, v[160:161]
	global_store_dwordx4 v[44:45], v[28:31], off offset:256 sc1
	v_cvt_pk_bf16_f32 v15, v10, v11
	v_mad_i64_i32 v[8:9], s[50:51], v8, s4, v[162:163]
	v_lshl_add_u64 v[28:29], v[24:25], 0, v[160:161]
	v_cvt_pk_bf16_f32 v124, v124, v125
	v_cvt_pk_bf16_f32 v125, v126, v127
	v_cvt_pk_bf16_f32 v126, v120, v121
	v_cvt_pk_bf16_f32 v127, v122, v123
	v_cvt_pk_bf16_f32 v104, v116, v117
	v_cvt_pk_bf16_f32 v105, v118, v119
	v_cvt_pk_bf16_f32 v106, v112, v113
	v_cvt_pk_bf16_f32 v107, v114, v115
	v_cvt_pk_bf16_f32 v88, v100, v101
	v_cvt_pk_bf16_f32 v89, v102, v103
	v_cvt_pk_bf16_f32 v90, v96, v97
	v_cvt_pk_bf16_f32 v91, v98, v99
	global_store_dwordx4 v[92:93], v[76:79], off offset:256 sc1
	v_cvt_pk_bf16_f32 v74, v80, v81
	v_cvt_pk_bf16_f32 v75, v82, v83
	v_lshl_add_u64 v[76:77], v[72:73], 0, v[160:161]
	v_cvt_pk_bf16_f32 v72, v84, v85
	v_cvt_pk_bf16_f32 v73, v86, v87
	v_cvt_pk_bf16_f32 v71, v66, v67
	v_cvt_pk_bf16_f32 v60, v60, v61
	v_cvt_pk_bf16_f32 v61, v62, v63
	v_cvt_pk_bf16_f32 v62, v56, v57
	v_cvt_pk_bf16_f32 v63, v58, v59
	v_cvt_pk_bf16_f32 v40, v52, v53
	v_cvt_pk_bf16_f32 v41, v54, v55
	v_cvt_pk_bf16_f32 v42, v48, v49
	v_cvt_pk_bf16_f32 v43, v50, v51
	v_cvt_pk_bf16_f32 v24, v36, v37
	v_cvt_pk_bf16_f32 v25, v38, v39
	v_cvt_pk_bf16_f32 v26, v32, v33
	v_cvt_pk_bf16_f32 v27, v34, v35
	global_store_dwordx4 v[28:29], v[12:15], off offset:256 sc1
	v_cvt_pk_bf16_f32 v10, v16, v17
	v_cvt_pk_bf16_f32 v11, v18, v19
	v_lshl_add_u64 v[12:13], v[8:9], 0, v[160:161]
	v_cvt_pk_bf16_f32 v8, v20, v21
	v_cvt_pk_bf16_f32 v9, v22, v23
	v_cvt_pk_bf16_f32 v4, v4, v5
	v_cvt_pk_bf16_f32 v5, v6, v7
	v_cvt_pk_bf16_f32 v6, v0, v1
	v_cvt_pk_bf16_f32 v7, v2, v3
	s_and_b64 vcc, exec, s[0:1]
	s_mov_b32 s68, s42
	s_mov_b32 s40, s44
	s_mov_b64 s[52:53], s[48:49]
	s_mov_b64 s[50:51], s[46:47]
	global_store_dwordx4 v[164:165], v[124:127], off sc1
	global_store_dwordx4 v[108:109], v[104:107], off sc1
	global_store_dwordx4 v[92:93], v[88:91], off sc1
	global_store_dwordx4 v[76:77], v[72:75], off sc1
	global_store_dwordx4 v[76:77], v[68:71], off offset:256 sc1
	global_store_dwordx4 v[64:65], v[60:63], off sc1
	global_store_dwordx4 v[44:45], v[40:43], off sc1
	global_store_dwordx4 v[28:29], v[24:27], off sc1
	global_store_dwordx4 v[12:13], v[8:11], off sc1
	global_store_dwordx4 v[12:13], v[4:7], off offset:256 sc1
	s_cbranch_vccz .LBB0_178
	s_waitcnt vmcnt(0)
	s_cmpk_gt_u32 s3, 0xff
	s_cbranch_scc1 .LBB0_185
	s_barrier
